# phase-1 tile decode mixes Q/K/V n-tiles across XCD parity and across each workgroup's tile sequence (balances rotary-epilogue cost)
# speedup vs baseline: 1.0926x; 1.0017x over previous
.LBB0_207:
	s_ashr_i32 s0, s64, 3
	s_lshr_b32 s1, s0, 28
	s_add_i32 s1, s0, s1
	s_and_b32 s5, s1, -16
	s_and_b32 s4, s64, 1
	s_sub_i32 s26, s0, s5
	s_lshr_b32 s5, s0, 6
	s_mul_i32 s5, s5, 5
	s_add_i32 s26, s26, s5
	s_and_b32 s26, s26, 15
	s_lshl_b32 s0, s1, 6
	s_lshl_b32 s1, s64, 7
	s_lshl_b32 s26, s26, 1
	s_and_b32 s0, s0, 0xfffffc00
	s_and_b32 s1, s1, 0x300
	s_or_b32 s26, s26, s4
	s_or_b32 s4, s0, s1
	s_ashr_i32 s5, s4, 31
	s_lshl_b32 s0, s26, 7
	s_lshl_b64 s[52:53], s[4:5], 11
	s_add_u32 s52, s3, s52
	s_addc_u32 s53, s34, s53
	s_ashr_i32 s1, s0, 31
	v_mov_b32_e32 v34, v220
	s_lshl_b64 s[54:55], s[0:1], 11
	s_add_u32 s54, s72, s54
	v_ashrrev_i32_e32 v24, 2, v34
	v_ashrrev_i32_e32 v25, 31, v24
	s_addc_u32 s55, s73, s55
	v_lshlrev_b64 v[0:1], 11, v[24:25]
	v_lshlrev_b32_e32 v4, 4, v34
	v_lshl_add_u64 v[2:3], s[54:55], 0, v[0:1]
	v_lshl_add_u64 v[0:1], s[52:53], 0, v[0:1]
	v_and_b32_e32 v152, 48, v4
	v_lshl_add_u64 v[154:155], v[0:1], 0, v[152:153]
	v_add_co_u32_e32 v26, vcc, s35, v154
	v_lshl_add_u64 v[156:157], v[2:3], 0, v[152:153]
	s_nop 0
	v_addc_co_u32_e32 v27, vcc, 0, v155, vcc
	v_add_co_u32_e32 v28, vcc, s36, v154
	global_load_dwordx4 v[0:3], v[154:155], off
	s_nop 0
	v_addc_co_u32_e32 v29, vcc, 0, v155, vcc
	v_add_co_u32_e32 v30, vcc, s37, v154
	global_load_dwordx4 v[4:7], v[26:27], off
	global_load_dwordx4 v[8:11], v[28:29], off
	v_addc_co_u32_e32 v31, vcc, 0, v155, vcc
	v_add_co_u32_e32 v32, vcc, s35, v156
	global_load_dwordx4 v[12:15], v[30:31], off
	global_load_dwordx4 v[16:19], v[156:157], off
	v_addc_co_u32_e32 v33, vcc, 0, v157, vcc
	global_load_dwordx4 v[20:23], v[32:33], off
	global_load_dwordx4 v[128:131], v[154:155], off offset:64
	global_load_dwordx4 v[136:139], v[26:27], off offset:64
	global_load_dwordx4 v[140:143], v[28:29], off offset:64
	global_load_dwordx4 v[144:147], v[30:31], off offset:64
	global_load_dwordx4 v[132:135], v[156:157], off offset:64
	global_load_dwordx4 v[148:151], v[32:33], off offset:64
	v_lshrrev_b32_e32 v35, 4, v34
	v_lshrrev_b32_e32 v36, 2, v34
	v_sub_u32_e32 v39, 0, v35
	v_sub_u32_e32 v36, 0, v36
	v_and_b32_e32 v37, 0x3ffff8f, v34
	v_lshlrev_b32_e32 v38, 6, v34
	v_xor_b32_e32 v34, v34, v39
	v_xor_b32_e32 v35, v35, v36
	v_lshlrev_b32_e32 v34, 4, v34
	v_lshlrev_b32_e32 v35, 4, v35
	v_mov_b32_e32 v25, 0x4000
	v_and_b32_e32 v40, 0x1000, v38
	v_and_b32_e32 v34, 48, v34
	v_and_b32_e32 v35, 48, v35
	v_and_b32_e32 v41, 0x3c0, v38
	v_and_b32_e32 v38, 0xffffe3c0, v38
	v_lshl_add_u32 v25, v37, 6, v25
	v_lshl_or_b32 v152, v24, 6, v34
	v_or_b32_e32 v24, v35, v40
	s_mov_b32 s1, -2
	v_or3_b32 v175, v40, v41, v35
	v_add_u32_e32 v176, v35, v38
	v_add_u32_e32 v177, v35, v25
	v_add_u32_e32 v178, v24, v41
	v_lshl_add_u64 v[158:159], v[154:155], 0, s[22:23]
	v_lshl_add_u64 v[160:161], v[154:155], 0, s[24:25]
	v_lshl_add_u64 v[162:163], v[154:155], 0, s[28:29]
	v_lshl_add_u64 v[164:165], v[156:157], 0, s[22:23]
	s_mov_b32 s5, s31
	v_mov_b32_e32 v64, 0
	v_mov_b32_e32 v65, v153
	v_mov_b32_e32 v66, v153
	v_mov_b32_e32 v67, v153
	v_mov_b32_e32 v68, 0
	v_mov_b32_e32 v69, v153
	v_mov_b32_e32 v70, v153
	v_mov_b32_e32 v71, v153
	v_mov_b32_e32 v72, 0
	v_mov_b32_e32 v73, v153
	v_mov_b32_e32 v74, v153
	v_mov_b32_e32 v75, v153
	v_mov_b32_e32 v76, 0
	v_mov_b32_e32 v77, v153
	v_mov_b32_e32 v78, v153
	v_mov_b32_e32 v79, v153
	v_mov_b32_e32 v80, 0
	s_waitcnt vmcnt(11)
	ds_write_b128 v152, v[0:3]
	s_waitcnt vmcnt(10)
	ds_write_b128 v152, v[4:7] offset:4096
	s_waitcnt vmcnt(9)
	ds_write_b128 v152, v[8:11] offset:8192
	s_waitcnt vmcnt(8)
	ds_write_b128 v152, v[12:15] offset:12288
	s_waitcnt vmcnt(7)
	ds_write_b128 v152, v[16:19] offset:32768
	s_waitcnt vmcnt(6)
	ds_write_b128 v152, v[20:23] offset:36864
	v_mov_b32_e32 v0, 0
	v_mov_b32_e32 v1, v153
	v_mov_b32_e32 v2, v153
	v_mov_b32_e32 v3, v153
	v_mov_b32_e32 v4, 0
	v_mov_b32_e32 v5, v153
	v_mov_b32_e32 v6, v153
	v_mov_b32_e32 v7, v153
	v_mov_b32_e32 v8, 0
	v_mov_b32_e32 v9, v153
	v_mov_b32_e32 v10, v153
	v_mov_b32_e32 v11, v153
	v_mov_b32_e32 v12, 0
	v_mov_b32_e32 v13, v153
	v_mov_b32_e32 v14, v153
	v_mov_b32_e32 v15, v153
	v_mov_b32_e32 v16, 0
	v_mov_b32_e32 v17, v153
	v_mov_b32_e32 v18, v153
	v_mov_b32_e32 v19, v153
	v_mov_b32_e32 v20, 0
	v_mov_b32_e32 v21, v153
	v_mov_b32_e32 v22, v153
	v_mov_b32_e32 v23, v153
	v_mov_b32_e32 v81, v153
	v_mov_b32_e32 v82, v153
	v_mov_b32_e32 v83, v153
	v_mov_b32_e32 v84, 0
	v_mov_b32_e32 v85, v153
	v_mov_b32_e32 v86, v153
	v_mov_b32_e32 v87, v153
	v_mov_b32_e32 v24, 0
	v_mov_b32_e32 v25, v153
	v_mov_b32_e32 v26, v153
	v_mov_b32_e32 v27, v153
	v_mov_b32_e32 v28, 0
	v_mov_b32_e32 v29, v153
	v_mov_b32_e32 v30, v153
	v_mov_b32_e32 v31, v153
	v_mov_b32_e32 v88, 0
	v_mov_b32_e32 v89, v153
	v_mov_b32_e32 v90, v153
	v_mov_b32_e32 v91, v153
	v_mov_b32_e32 v92, 0
	v_mov_b32_e32 v93, v153
	v_mov_b32_e32 v94, v153
	v_mov_b32_e32 v95, v153
	v_mov_b32_e32 v32, 0
	v_mov_b32_e32 v33, v153
	v_mov_b32_e32 v34, v153
	v_mov_b32_e32 v35, v153
	v_mov_b32_e32 v36, 0
	v_mov_b32_e32 v37, v153
	v_mov_b32_e32 v38, v153
	v_mov_b32_e32 v39, v153
	v_mov_b32_e32 v96, 0
	v_mov_b32_e32 v97, v153
	v_mov_b32_e32 v98, v153
	v_mov_b32_e32 v99, v153
	v_mov_b32_e32 v100, 0
	v_mov_b32_e32 v101, v153
	v_mov_b32_e32 v102, v153
	v_mov_b32_e32 v103, v153
	v_mov_b32_e32 v40, 0
	v_mov_b32_e32 v41, v153
	v_mov_b32_e32 v42, v153
	v_mov_b32_e32 v43, v153
	v_mov_b32_e32 v44, 0
	v_mov_b32_e32 v45, v153
	v_mov_b32_e32 v46, v153
	v_mov_b32_e32 v47, v153
	v_mov_b32_e32 v104, 0
	v_mov_b32_e32 v105, v153
	v_mov_b32_e32 v106, v153
	v_mov_b32_e32 v107, v153
	v_mov_b32_e32 v108, 0
	v_mov_b32_e32 v109, v153
	v_mov_b32_e32 v110, v153
	v_mov_b32_e32 v111, v153
	v_mov_b32_e32 v48, 0
	v_mov_b32_e32 v49, v153
	v_mov_b32_e32 v50, v153
	v_mov_b32_e32 v51, v153
	v_mov_b32_e32 v52, 0
	v_mov_b32_e32 v53, v153
	v_mov_b32_e32 v54, v153
	v_mov_b32_e32 v55, v153
	v_mov_b32_e32 v112, 0
	v_mov_b32_e32 v113, v153
	v_mov_b32_e32 v114, v153
	v_mov_b32_e32 v115, v153
	v_mov_b32_e32 v116, 0
	v_mov_b32_e32 v117, v153
	v_mov_b32_e32 v118, v153
	v_mov_b32_e32 v119, v153
	v_mov_b32_e32 v56, 0
	v_mov_b32_e32 v57, v153
	v_mov_b32_e32 v58, v153
	v_mov_b32_e32 v59, v153
	v_mov_b32_e32 v60, 0
	v_mov_b32_e32 v61, v153
	v_mov_b32_e32 v62, v153
	v_mov_b32_e32 v63, v153
	v_mov_b32_e32 v120, 0
	v_mov_b32_e32 v121, v153
	v_mov_b32_e32 v122, v153
	v_mov_b32_e32 v123, v153
	v_mov_b32_e32 v124, 0
	v_mov_b32_e32 v125, v153
	v_mov_b32_e32 v126, v153
	v_mov_b32_e32 v127, v153
	s_waitcnt lgkmcnt(0)
	s_barrier
